# 8 of 20 grid seams (GU->DN, DN->PLE, PLE->GU, DN->Rin ...) replaced by XCD-group-local barriers (row ownership is per logical XCD group; runtime census check with fallback to the global barrier)
# speedup vs baseline: 1.0254x; 1.0254x over previous
; #define LAS __attribute__((address_space(3)))
; __device__ __forceinline__ unsigned xb_add(unsigned* p, unsigned v) { return __hip_atomic_fetch_add(p, v, __ATOMIC_RELAXED, __HIP_MEMORY_SCOPE_AGENT); }
; __device__ __forceinline__ unsigned xb_xcc_id() { return (unsigned)__builtin_amdgcn_s_getreg((3 << 11) | 20) & 0xFu; }
; __global__ void __launch_bounds__(512, 2) mk_fwd(Args args) {
;     extern __shared__ __attribute__((aligned(16))) unsigned char lds_raw[];
;     LAS unsigned char* lds = (LAS unsigned char*)lds_raw;
;     const int G = gridDim.x;
;     const int wave_s = __builtin_amdgcn_readfirstlane(threadIdx.x >> 6);
;     const int lo = args.ph_lo, hi = args.ph_hi;
;     if (threadIdx.x < 16) ((LAS unsigned*)(lds + 131072))[threadIdx.x] = 0u;
;     if (hi - lo > 1) {
;         if (threadIdx.x == 0) (void)xb_add(&((unsigned*)args.ws)[XB_XCNT(xb_xcc_id())], 1u);
;         cg::this_grid().sync();
;     }
;     __syncthreads();
_Z6mk_fwd4Args:
	s_load_dwordx2 s[94:95], s[0:1], 0x638
	s_add_u32 s4, s0, 0x648
	v_and_b32_e32 v1, 0x3ff, v0
	s_mov_b32 s78, s2
	s_mov_b32 s98, 0
	s_addc_u32 s5, s1, 0
	v_readfirstlane_b32 s79, v1
	v_cmp_gt_u32_e32 vcc, 16, v1
	s_and_saveexec_b64 s[2:3], vcc
	v_lshl_add_u32 v2, v1, 2, 0
	v_add_u32_e32 v2, 0x20000, v2
	v_mov_b32_e32 v3, 0
	ds_write_b32 v2, v3
	s_or_b64 exec, exec, s[2:3]
	s_load_dword s92, s[0:1], 0x648
	s_waitcnt lgkmcnt(0)
	s_sub_i32 s2, s95, s94
	s_cmp_lt_i32 s2, 2
	s_cbranch_scc1 .LBB0_17
	v_cmp_eq_u32_e32 vcc, 0, v1
	s_and_saveexec_b64 s[2:3], vcc
	s_cbranch_execz .LBB0_6
	s_mov_b64 s[6:7], exec
	v_mbcnt_lo_u32_b32 v2, s6, 0
	v_mbcnt_hi_u32_b32 v2, s7, v2
	v_cmp_eq_u32_e32 vcc, 0, v2
	s_getreg_b32 s8, hwreg(HW_REG_XCC_ID, 0, 4)
	s_and_b64 s[10:11], exec, vcc
	s_mov_b64 exec, s[10:11]
	s_cbranch_execz .LBB0_6
	s_load_dwordx2 s[10:11], s[0:1], 0xf0
	s_lshl_b32 s8, s8, 8
	s_and_b32 s8, s8, 0xf00
	s_bcnt1_i32_b64 s6, s[6:7]
	v_mov_b32_e32 v2, s8
	v_mov_b32_e32 v3, s6
	s_waitcnt lgkmcnt(0)
	global_atomic_add v2, v3, s[10:11] offset:1024
	s_lshr_b32 s8, s8, 8
	s_lshl_b32 s8, 1, s8
	s_and_b32 s6, s78, 7
	s_lshl_b32 s6, s6, 8
	v_mov_b32_e32 v2, s6
	v_mov_b32_e32 v3, s8
	global_atomic_or v2, v3, s[10:11] offset:1088

; #define LAS __attribute__((address_space(3)))
; __device__ __forceinline__ unsigned xb_add(unsigned* p, unsigned v) { return __hip_atomic_fetch_add(p, v, __ATOMIC_RELAXED, __HIP_MEMORY_SCOPE_AGENT); }
; __device__ __forceinline__ unsigned xb_xcc_id() { return (unsigned)__builtin_amdgcn_s_getreg((3 << 11) | 20) & 0xFu; }
; __global__ void __launch_bounds__(512, 2) mk_fwd(Args args) {
;     ...
;     const int lo = args.ph_lo, hi = args.ph_hi;
;     if (threadIdx.x < 16) ((LAS unsigned*)(lds + 131072))[threadIdx.x] = 0u;
;     if (hi - lo > 1) {
;         if (threadIdx.x == 0) (void)xb_add(&((unsigned*)args.ws)[XB_XCNT(xb_xcc_id())], 1u);
;         cg::this_grid().sync();
;     }
;     __syncthreads();
.LBB0_251:
	s_or_b64 exec, exec, s[2:3]
	s_waitcnt lgkmcnt(0)
	s_barrier
	s_load_dwordx2 s[4:5], s[0:1], 0xf0
	v_mov_b32_e32 v0, 0
	s_waitcnt lgkmcnt(0)
	global_load_dword v1, v0, s[4:5] offset:1088 sc1
	global_load_dword v2, v0, s[4:5] offset:1344 sc1
	global_load_dword v3, v0, s[4:5] offset:1600 sc1
	global_load_dword v4, v0, s[4:5] offset:1856 sc1
	global_load_dword v5, v0, s[4:5] offset:2112 sc1
	global_load_dword v6, v0, s[4:5] offset:2368 sc1
	global_load_dword v7, v0, s[4:5] offset:2624 sc1
	global_load_dword v8, v0, s[4:5] offset:2880 sc1
	s_waitcnt vmcnt(0)
	s_mov_b32 s98, 1
	v_readfirstlane_b32 s6, v1
	s_add_u32 s7, s6, -1
	s_and_b32 s7, s7, s6
	s_cmp_lg_u32 s7, 0
	s_cselect_b32 s98, 0, s98
	s_cmp_eq_u32 s6, 0
	s_cselect_b32 s98, 0, s98
	v_readfirstlane_b32 s6, v2
	s_add_u32 s7, s6, -1
	s_and_b32 s7, s7, s6
	s_cmp_lg_u32 s7, 0
	s_cselect_b32 s98, 0, s98
	s_cmp_eq_u32 s6, 0
	s_cselect_b32 s98, 0, s98
	v_readfirstlane_b32 s6, v3
	s_add_u32 s7, s6, -1
	s_and_b32 s7, s7, s6
	s_cmp_lg_u32 s7, 0
	s_cselect_b32 s98, 0, s98
	s_cmp_eq_u32 s6, 0
	s_cselect_b32 s98, 0, s98
	v_readfirstlane_b32 s6, v4
	s_add_u32 s7, s6, -1
	s_and_b32 s7, s7, s6
	s_cmp_lg_u32 s7, 0
	s_cselect_b32 s98, 0, s98
	s_cmp_eq_u32 s6, 0
	s_cselect_b32 s98, 0, s98
	v_readfirstlane_b32 s6, v5
	s_add_u32 s7, s6, -1
	s_and_b32 s7, s7, s6
	s_cmp_lg_u32 s7, 0
	s_cselect_b32 s98, 0, s98
	s_cmp_eq_u32 s6, 0
	s_cselect_b32 s98, 0, s98
	v_readfirstlane_b32 s6, v6
	s_add_u32 s7, s6, -1
	s_and_b32 s7, s7, s6
	s_cmp_lg_u32 s7, 0
	s_cselect_b32 s98, 0, s98
	s_cmp_eq_u32 s6, 0
	s_cselect_b32 s98, 0, s98
	v_readfirstlane_b32 s6, v7
	s_add_u32 s7, s6, -1
	s_and_b32 s7, s7, s6
	s_cmp_lg_u32 s7, 0
	s_cselect_b32 s98, 0, s98
	s_cmp_eq_u32 s6, 0
	s_cselect_b32 s98, 0, s98
	v_readfirstlane_b32 s6, v8
	s_add_u32 s7, s6, -1
	s_and_b32 s7, s7, s6
	s_cmp_lg_u32 s7, 0
	s_cselect_b32 s98, 0, s98
	s_cmp_eq_u32 s6, 0
	s_cselect_b32 s98, 0, s98
	s_and_b32 s7, s92, 7
	s_cmp_lg_u32 s7, 0
	s_cselect_b32 s98, 0, s98

; #define LAS __attribute__((address_space(3)))
; __device__ __forceinline__ unsigned xb_ld(unsigned* p)              { return __hip_atomic_load(p, __ATOMIC_RELAXED, __HIP_MEMORY_SCOPE_AGENT); }
; __device__ __forceinline__ unsigned xb_add(unsigned* p, unsigned v) { return __hip_atomic_fetch_add(p, v, __ATOMIC_RELAXED, __HIP_MEMORY_SCOPE_AGENT); }
; __device__ __forceinline__ unsigned xb_xcc_id() { return (unsigned)__builtin_amdgcn_s_getreg((3 << 11) | 20) & 0xFu; }
; #define XB_SPIN(cond, bar) do { unsigned _sp = 0; while (cond) { __builtin_amdgcn_s_sleep(1); \
;     if ((++_sp & 255u) == 0u) { if (xb_ld(&(bar)[XB_TMO])) break; if (_sp > XB_SPIN_CAP) { atomicAdd(&(bar)[XB_TMO], 1u); break; } } } } while (0)
; __device__ __forceinline__ bool is_leader(int wave_s) { int lane; asm volatile("v_mbcnt_lo_u32_b32 %0, -1, 0\n\tv_mbcnt_hi_u32_b32 %0, -1, %0" : "=v"(lane)); return wave_s == 0 && lane == 0; }
; __device__ __forceinline__ void grid_bar(unsigned* bar, volatile LAS unsigned* st, int wave_s, unsigned G) {
;     asm volatile("s_waitcnt vmcnt(0) lgkmcnt(0)" ::: "memory");
;     __syncthreads();
;     if (is_leader(wave_s)) {
;         const unsigned x = xb_xcc_id();
;         unsigned nloc = st[0], nx = st[1];
;         if (nloc == 0u) { xcd_barrier_complete(bar, x, G, nloc, nx); st[0] = nloc; st[1] = nx; }
;         const unsigned old = xb_add(&bar[XB_XSUB(x)], 1u);
;         const unsigned gen = old / nloc;
;         if (old + 1u == (gen + 1u) * nloc) {
;             __builtin_amdgcn_fence(__ATOMIC_RELEASE, "agent");
;             asm volatile("s_waitcnt vmcnt(0)" ::: "memory");
;             const unsigned og = xb_add(&bar[XB_TOP], 1u);
;             const unsigned tg = og / nx;
;             if (og + 1u == (tg + 1u) * nx) xb_add(&bar[XB_TOPGEN], 1u);
;             else XB_SPIN(xb_ld(&bar[XB_TOPGEN]) == tg, bar);
;             __builtin_amdgcn_fence(__ATOMIC_ACQUIRE, "agent");
;             xb_add(&bar[XB_XGEN(x)], 1u);
;             asm volatile("s_waitcnt vmcnt(0)" ::: "memory");
;         } else {
;             XB_SPIN(xb_ld(&bar[XB_XGEN(x)]) == gen, bar);
;             __builtin_amdgcn_fence(__ATOMIC_ACQUIRE, "agent");
;             asm volatile("s_waitcnt vmcnt(0)" ::: "memory");
;         }
;     }
;     __syncthreads();
; }
.LBB0_272:
	s_mov_b32 s4, s95
	s_mov_b32 s2, s94
	s_cmp_lt_i32 s2, 2
	s_cselect_b64 s[2:3], -1, 0
	s_cmp_gt_i32 s4, 1
	s_cselect_b64 s[4:5], -1, 0
	s_and_b64 s[2:3], s[2:3], s[4:5]
	s_andn2_b64 vcc, exec, s[2:3]
	s_cbranch_vccnz .LBB0_327
	s_mov_b32 s2, s94
	s_mov_b32 s4, s95
	s_cmp_lt_i32 s2, 3
	s_cselect_b64 s[2:3], -1, 0
	s_cmp_gt_i32 s4, 2
	s_cselect_b64 s[4:5], -1, 0
	s_and_b64 s[2:3], s[2:3], s[4:5]
	s_andn2_b64 vcc, exec, s[2:3]
	s_cbranch_vccnz .LBB0_327
	s_cmp_lt_u32 s79, 64
	s_waitcnt vmcnt(0) lgkmcnt(0)
	s_cselect_b64 s[2:3], -1, 0
	s_waitcnt vmcnt(0) lgkmcnt(0)
	s_barrier
	v_mbcnt_lo_u32_b32 v0, -1, 0
	v_mbcnt_hi_u32_b32 v0, -1, v0
	s_nop 0
	v_cmp_eq_u32_e32 vcc, 0, v0
	s_and_b64 s[4:5], s[2:3], vcc
	s_and_saveexec_b64 s[2:3], s[4:5]
	s_cbranch_execz .LBB0_326
	s_cmp_eq_u32 s98, 0
	s_cbranch_scc1 .Lgl_1
	s_load_dwordx2 s[4:5], s[0:1], 0xf0
	s_and_b32 s6, s78, 7
	s_lshl_b32 s6, s6, 8
	s_lshr_b32 s7, s92, 3
	s_mul_i32 s7, s7, 1
	v_mov_b32_e32 v0, s6
	v_mov_b32_e32 v1, 1
	s_waitcnt lgkmcnt(0)
	global_atomic_add v2, v0, v1, s[4:5] offset:1152 sc0
	s_waitcnt vmcnt(0)
	v_readfirstlane_b32 s8, v2
	s_add_i32 s8, s8, 1
	s_cmp_eq_u32 s8, s7
	s_cbranch_scc0 .Lwt_1
	global_atomic_add v0, v1, s[4:5] offset:1216
	s_branch .Lac_1
.Lwt_1:
	s_sleep 1
	global_load_dword v2, v0, s[4:5] offset:1216 sc1
	s_waitcnt vmcnt(0)
	v_readfirstlane_b32 s8, v2
	s_cmp_lt_u32 s8, 1
	s_cbranch_scc1 .Lwt_1
.Lac_1:
	s_waitcnt vmcnt(0)
	buffer_inv sc1
	s_waitcnt vmcnt(0)
	s_branch .LBB0_326
.Lgl_1:
	s_add_i32 s7, 0, 0x20000
	v_mov_b32_e32 v0, s7
	s_getreg_b32 s6, hwreg(HW_REG_XCC_ID, 0, 4)
	ds_read_b32 v2, v0
	s_add_i32 s7, 0, 0x20004
	v_mov_b32_e32 v0, s7
	s_load_dwordx2 s[4:5], s[0:1], 0xf0
	ds_read_b32 v0, v0
	s_waitcnt lgkmcnt(0)
	v_cmp_ne_u32_e32 vcc, 0, v2
	s_and_b32 s20, s6, 15
	s_cbranch_vccnz .LBB0_290
	s_add_u32 s6, s4, 0x1000
	s_addc_u32 s7, s5, 0
	s_add_u32 s8, s4, 0x1100
	s_addc_u32 s9, s5, 0
	s_add_u32 s10, s4, 0x1200
	s_addc_u32 s11, s5, 0
	s_add_u32 s12, s4, 0x1300
	s_addc_u32 s13, s5, 0
	s_mov_b32 s21, 1
	v_mov_b32_e32 v16, 0
	s_branch .LBB0_278

; #define LAS __attribute__((address_space(3)))
; __device__ __forceinline__ unsigned xb_ld(unsigned* p)              { return __hip_atomic_load(p, __ATOMIC_RELAXED, __HIP_MEMORY_SCOPE_AGENT); }
; __device__ __forceinline__ unsigned xb_add(unsigned* p, unsigned v) { return __hip_atomic_fetch_add(p, v, __ATOMIC_RELAXED, __HIP_MEMORY_SCOPE_AGENT); }
; __device__ __forceinline__ unsigned xb_xcc_id() { return (unsigned)__builtin_amdgcn_s_getreg((3 << 11) | 20) & 0xFu; }
; #define XB_SPIN(cond, bar) do { unsigned _sp = 0; while (cond) { __builtin_amdgcn_s_sleep(1); \
;     if ((++_sp & 255u) == 0u) { if (xb_ld(&(bar)[XB_TMO])) break; if (_sp > XB_SPIN_CAP) { atomicAdd(&(bar)[XB_TMO], 1u); break; } } } } while (0)
; __device__ __forceinline__ bool is_leader(int wave_s) { int lane; asm volatile("v_mbcnt_lo_u32_b32 %0, -1, 0\n\tv_mbcnt_hi_u32_b32 %0, -1, %0" : "=v"(lane)); return wave_s == 0 && lane == 0; }
; __device__ __forceinline__ void grid_bar(unsigned* bar, volatile LAS unsigned* st, int wave_s, unsigned G) {
;     asm volatile("s_waitcnt vmcnt(0) lgkmcnt(0)" ::: "memory");
;     __syncthreads();
;     if (is_leader(wave_s)) {
;         const unsigned x = xb_xcc_id();
;         unsigned nloc = st[0], nx = st[1];
;         if (nloc == 0u) { xcd_barrier_complete(bar, x, G, nloc, nx); st[0] = nloc; st[1] = nx; }
;         const unsigned old = xb_add(&bar[XB_XSUB(x)], 1u);
;         const unsigned gen = old / nloc;
;         if (old + 1u == (gen + 1u) * nloc) {
;             __builtin_amdgcn_fence(__ATOMIC_RELEASE, "agent");
;             asm volatile("s_waitcnt vmcnt(0)" ::: "memory");
;             const unsigned og = xb_add(&bar[XB_TOP], 1u);
;             const unsigned tg = og / nx;
;             if (og + 1u == (tg + 1u) * nx) xb_add(&bar[XB_TOPGEN], 1u);
;             else XB_SPIN(xb_ld(&bar[XB_TOPGEN]) == tg, bar);
;             __builtin_amdgcn_fence(__ATOMIC_ACQUIRE, "agent");
;             xb_add(&bar[XB_XGEN(x)], 1u);
;             asm volatile("s_waitcnt vmcnt(0)" ::: "memory");
;         } else {
;             XB_SPIN(xb_ld(&bar[XB_XGEN(x)]) == gen, bar);
;             __builtin_amdgcn_fence(__ATOMIC_ACQUIRE, "agent");
;             asm volatile("s_waitcnt vmcnt(0)" ::: "memory");
;         }
;     }
;     __syncthreads();
; }
.LBB0_826:
	s_mov_b32 s2, s94
	s_mov_b32 s4, s95
	s_cmp_lt_i32 s2, 8
	s_cselect_b64 s[2:3], -1, 0
	s_cmp_gt_i32 s4, 7
	s_cselect_b64 s[4:5], -1, 0
	s_and_b64 s[2:3], s[2:3], s[4:5]
	s_andn2_b64 vcc, exec, s[2:3]
	s_cbranch_vccnz .LBB0_881
	s_mov_b32 s2, s94
	s_mov_b32 s4, s95
	s_cmp_lt_i32 s2, 9
	s_cselect_b64 s[2:3], -1, 0
	s_cmp_gt_i32 s4, 8
	s_cselect_b64 s[4:5], -1, 0
	s_and_b64 s[2:3], s[2:3], s[4:5]
	s_andn2_b64 vcc, exec, s[2:3]
	s_cbranch_vccnz .LBB0_881
	s_cmp_lt_u32 s79, 64
	s_waitcnt vmcnt(0) lgkmcnt(0)
	s_cselect_b64 s[2:3], -1, 0
	s_waitcnt vmcnt(0) lgkmcnt(0)
	s_barrier
	v_mbcnt_lo_u32_b32 v0, -1, 0
	v_mbcnt_hi_u32_b32 v0, -1, v0
	s_nop 0
	v_cmp_eq_u32_e32 vcc, 0, v0
	s_and_b64 s[4:5], s[2:3], vcc
	s_and_saveexec_b64 s[2:3], s[4:5]
	s_cbranch_execz .LBB0_880
	s_cmp_eq_u32 s98, 0
	s_cbranch_scc1 .Lgl_2
	s_load_dwordx2 s[4:5], s[0:1], 0xf0
	s_and_b32 s6, s78, 7
	s_lshl_b32 s6, s6, 8
	s_lshr_b32 s7, s92, 3
	s_mul_i32 s7, s7, 2
	v_mov_b32_e32 v0, s6
	v_mov_b32_e32 v1, 1
	s_waitcnt lgkmcnt(0)
	global_atomic_add v2, v0, v1, s[4:5] offset:1152 sc0
	s_waitcnt vmcnt(0)
	v_readfirstlane_b32 s8, v2
	s_add_i32 s8, s8, 1
	s_cmp_eq_u32 s8, s7
	s_cbranch_scc0 .Lwt_2
	global_atomic_add v0, v1, s[4:5] offset:1216
	s_branch .Lac_2
.Lwt_2:
	s_sleep 1
	global_load_dword v2, v0, s[4:5] offset:1216 sc1
	s_waitcnt vmcnt(0)
	v_readfirstlane_b32 s8, v2
	s_cmp_lt_u32 s8, 2
	s_cbranch_scc1 .Lwt_2

; #define LAS __attribute__((address_space(3)))
; __device__ __forceinline__ unsigned xb_ld(unsigned* p)              { return __hip_atomic_load(p, __ATOMIC_RELAXED, __HIP_MEMORY_SCOPE_AGENT); }
; __device__ __forceinline__ unsigned xb_add(unsigned* p, unsigned v) { return __hip_atomic_fetch_add(p, v, __ATOMIC_RELAXED, __HIP_MEMORY_SCOPE_AGENT); }
; __device__ __forceinline__ unsigned xb_xcc_id() { return (unsigned)__builtin_amdgcn_s_getreg((3 << 11) | 20) & 0xFu; }
; #define XB_SPIN(cond, bar) do { unsigned _sp = 0; while (cond) { __builtin_amdgcn_s_sleep(1); \
;     if ((++_sp & 255u) == 0u) { if (xb_ld(&(bar)[XB_TMO])) break; if (_sp > XB_SPIN_CAP) { atomicAdd(&(bar)[XB_TMO], 1u); break; } } } } while (0)
; __device__ __forceinline__ bool is_leader(int wave_s) { int lane; asm volatile("v_mbcnt_lo_u32_b32 %0, -1, 0\n\tv_mbcnt_hi_u32_b32 %0, -1, %0" : "=v"(lane)); return wave_s == 0 && lane == 0; }
; __device__ __forceinline__ void grid_bar(unsigned* bar, volatile LAS unsigned* st, int wave_s, unsigned G) {
;     asm volatile("s_waitcnt vmcnt(0) lgkmcnt(0)" ::: "memory");
;     __syncthreads();
;     if (is_leader(wave_s)) {
;         const unsigned x = xb_xcc_id();
;         unsigned nloc = st[0], nx = st[1];
;         if (nloc == 0u) { xcd_barrier_complete(bar, x, G, nloc, nx); st[0] = nloc; st[1] = nx; }
;         const unsigned old = xb_add(&bar[XB_XSUB(x)], 1u);
;         const unsigned gen = old / nloc;
;         if (old + 1u == (gen + 1u) * nloc) {
;             __builtin_amdgcn_fence(__ATOMIC_RELEASE, "agent");
;             asm volatile("s_waitcnt vmcnt(0)" ::: "memory");
;             const unsigned og = xb_add(&bar[XB_TOP], 1u);
;             const unsigned tg = og / nx;
;             if (og + 1u == (tg + 1u) * nx) xb_add(&bar[XB_TOPGEN], 1u);
;             else XB_SPIN(xb_ld(&bar[XB_TOPGEN]) == tg, bar);
;             __builtin_amdgcn_fence(__ATOMIC_ACQUIRE, "agent");
;             xb_add(&bar[XB_XGEN(x)], 1u);
;             asm volatile("s_waitcnt vmcnt(0)" ::: "memory");
;         } else {
;             XB_SPIN(xb_ld(&bar[XB_XGEN(x)]) == gen, bar);
;             __builtin_amdgcn_fence(__ATOMIC_ACQUIRE, "agent");
;             asm volatile("s_waitcnt vmcnt(0)" ::: "memory");
;         }
;     }
;     __syncthreads();
; }
.LBB0_956:
	s_mov_b32 s2, s94
	s_mov_b32 s4, s95
	s_cmp_lt_i32 s2, 9
	s_cselect_b64 s[2:3], -1, 0
	s_cmp_gt_i32 s4, 8
	s_cselect_b64 s[4:5], -1, 0
	s_and_b64 s[2:3], s[2:3], s[4:5]
	s_andn2_b64 vcc, exec, s[2:3]
	s_cbranch_vccnz .LBB0_1011
	s_mov_b32 s2, s94
	s_mov_b32 s4, s95
	s_cmp_lt_i32 s2, 10
	s_cselect_b64 s[2:3], -1, 0
	s_cmp_gt_i32 s4, 9
	s_cselect_b64 s[4:5], -1, 0
	s_and_b64 s[2:3], s[2:3], s[4:5]
	s_andn2_b64 vcc, exec, s[2:3]
	s_cbranch_vccnz .LBB0_1011
	s_cmp_lt_u32 s79, 64
	s_waitcnt vmcnt(0) lgkmcnt(0)
	s_cselect_b64 s[2:3], -1, 0
	s_waitcnt vmcnt(0) lgkmcnt(0)
	s_barrier
	v_mbcnt_lo_u32_b32 v0, -1, 0
	v_mbcnt_hi_u32_b32 v0, -1, v0
	s_nop 0
	v_cmp_eq_u32_e32 vcc, 0, v0
	s_and_b64 s[4:5], s[2:3], vcc
	s_and_saveexec_b64 s[2:3], s[4:5]
	s_cbranch_execz .LBB0_1010
	s_cmp_eq_u32 s98, 0
	s_cbranch_scc1 .Lgl_3
	s_load_dwordx2 s[4:5], s[0:1], 0xf0
	s_and_b32 s6, s78, 7
	s_lshl_b32 s6, s6, 8
	s_lshr_b32 s7, s92, 3
	s_mul_i32 s7, s7, 3
	v_mov_b32_e32 v0, s6
	v_mov_b32_e32 v1, 1
	s_waitcnt lgkmcnt(0)
	global_atomic_add v2, v0, v1, s[4:5] offset:1152 sc0
	s_waitcnt vmcnt(0)
	v_readfirstlane_b32 s8, v2
	s_add_i32 s8, s8, 1
	s_cmp_eq_u32 s8, s7
	s_cbranch_scc0 .Lwt_3
	global_atomic_add v0, v1, s[4:5] offset:1216
	s_branch .Lac_3
.Lwt_3:
	s_sleep 1
	global_load_dword v2, v0, s[4:5] offset:1216 sc1
	s_waitcnt vmcnt(0)
	v_readfirstlane_b32 s8, v2
	s_cmp_lt_u32 s8, 3
	s_cbranch_scc1 .Lwt_3

; #define LAS __attribute__((address_space(3)))
; __device__ __forceinline__ unsigned xb_ld(unsigned* p)              { return __hip_atomic_load(p, __ATOMIC_RELAXED, __HIP_MEMORY_SCOPE_AGENT); }
; __device__ __forceinline__ unsigned xb_add(unsigned* p, unsigned v) { return __hip_atomic_fetch_add(p, v, __ATOMIC_RELAXED, __HIP_MEMORY_SCOPE_AGENT); }
; __device__ __forceinline__ unsigned xb_xcc_id() { return (unsigned)__builtin_amdgcn_s_getreg((3 << 11) | 20) & 0xFu; }
; #define XB_SPIN(cond, bar) do { unsigned _sp = 0; while (cond) { __builtin_amdgcn_s_sleep(1); \
;     if ((++_sp & 255u) == 0u) { if (xb_ld(&(bar)[XB_TMO])) break; if (_sp > XB_SPIN_CAP) { atomicAdd(&(bar)[XB_TMO], 1u); break; } } } } while (0)
; __device__ __forceinline__ bool is_leader(int wave_s) { int lane; asm volatile("v_mbcnt_lo_u32_b32 %0, -1, 0\n\tv_mbcnt_hi_u32_b32 %0, -1, %0" : "=v"(lane)); return wave_s == 0 && lane == 0; }
; __device__ __forceinline__ void grid_bar(unsigned* bar, volatile LAS unsigned* st, int wave_s, unsigned G) {
;     asm volatile("s_waitcnt vmcnt(0) lgkmcnt(0)" ::: "memory");
;     __syncthreads();
;     if (is_leader(wave_s)) {
;         const unsigned x = xb_xcc_id();
;         unsigned nloc = st[0], nx = st[1];
;         if (nloc == 0u) { xcd_barrier_complete(bar, x, G, nloc, nx); st[0] = nloc; st[1] = nx; }
;         const unsigned old = xb_add(&bar[XB_XSUB(x)], 1u);
;         const unsigned gen = old / nloc;
;         if (old + 1u == (gen + 1u) * nloc) {
;             __builtin_amdgcn_fence(__ATOMIC_RELEASE, "agent");
;             asm volatile("s_waitcnt vmcnt(0)" ::: "memory");
;             const unsigned og = xb_add(&bar[XB_TOP], 1u);
;             const unsigned tg = og / nx;
;             if (og + 1u == (tg + 1u) * nx) xb_add(&bar[XB_TOPGEN], 1u);
;             else XB_SPIN(xb_ld(&bar[XB_TOPGEN]) == tg, bar);
;             __builtin_amdgcn_fence(__ATOMIC_ACQUIRE, "agent");
;             xb_add(&bar[XB_XGEN(x)], 1u);
;             asm volatile("s_waitcnt vmcnt(0)" ::: "memory");
;         } else {
;             XB_SPIN(xb_ld(&bar[XB_XGEN(x)]) == gen, bar);
;             __builtin_amdgcn_fence(__ATOMIC_ACQUIRE, "agent");
;             asm volatile("s_waitcnt vmcnt(0)" ::: "memory");
;         }
;     }
;     __syncthreads();
; }
.LBB0_1057:
	s_mov_b32 s2, s94
	s_mov_b32 s4, s95
	s_cmp_lt_i32 s2, 10
	s_cselect_b64 s[2:3], -1, 0
	s_cmp_gt_i32 s4, 9
	s_cselect_b64 s[4:5], -1, 0
	s_and_b64 s[2:3], s[2:3], s[4:5]
	s_andn2_b64 vcc, exec, s[2:3]
	s_cbranch_vccnz .LBB0_1112
	s_mov_b32 s2, s94
	s_mov_b32 s4, s95
	s_cmp_lt_i32 s2, 11
	s_cselect_b64 s[2:3], -1, 0
	s_cmp_gt_i32 s4, 10
	s_cselect_b64 s[4:5], -1, 0
	s_and_b64 s[2:3], s[2:3], s[4:5]
	s_andn2_b64 vcc, exec, s[2:3]
	s_cbranch_vccnz .LBB0_1112
	s_cmp_lt_u32 s79, 64
	s_waitcnt vmcnt(0) lgkmcnt(0)
	s_cselect_b64 s[2:3], -1, 0
	s_waitcnt vmcnt(0) lgkmcnt(0)
	s_barrier
	v_mbcnt_lo_u32_b32 v0, -1, 0
	v_mbcnt_hi_u32_b32 v0, -1, v0
	s_nop 0
	v_cmp_eq_u32_e32 vcc, 0, v0
	s_and_b64 s[4:5], s[2:3], vcc
	s_and_saveexec_b64 s[2:3], s[4:5]
	s_cbranch_execz .LBB0_1111
	s_cmp_eq_u32 s98, 0
	s_cbranch_scc1 .Lgl_4
	s_load_dwordx2 s[4:5], s[0:1], 0xf0
	s_and_b32 s6, s78, 7
	s_lshl_b32 s6, s6, 8
	s_lshr_b32 s7, s92, 3
	s_mul_i32 s7, s7, 4
	v_mov_b32_e32 v0, s6
	v_mov_b32_e32 v1, 1
	s_waitcnt lgkmcnt(0)
	global_atomic_add v2, v0, v1, s[4:5] offset:1152 sc0
	s_waitcnt vmcnt(0)
	v_readfirstlane_b32 s8, v2
	s_add_i32 s8, s8, 1
	s_cmp_eq_u32 s8, s7
	s_cbranch_scc0 .Lwt_4
	global_atomic_add v0, v1, s[4:5] offset:1216
	s_branch .Lac_4
.Lwt_4:
	s_sleep 1
	global_load_dword v2, v0, s[4:5] offset:1216 sc1
	s_waitcnt vmcnt(0)
	v_readfirstlane_b32 s8, v2
	s_cmp_lt_u32 s8, 4
	s_cbranch_scc1 .Lwt_4

; #define LAS __attribute__((address_space(3)))
; __device__ __forceinline__ unsigned xb_ld(unsigned* p)              { return __hip_atomic_load(p, __ATOMIC_RELAXED, __HIP_MEMORY_SCOPE_AGENT); }
; __device__ __forceinline__ unsigned xb_add(unsigned* p, unsigned v) { return __hip_atomic_fetch_add(p, v, __ATOMIC_RELAXED, __HIP_MEMORY_SCOPE_AGENT); }
; __device__ __forceinline__ unsigned xb_xcc_id() { return (unsigned)__builtin_amdgcn_s_getreg((3 << 11) | 20) & 0xFu; }
; #define XB_SPIN(cond, bar) do { unsigned _sp = 0; while (cond) { __builtin_amdgcn_s_sleep(1); \
;     if ((++_sp & 255u) == 0u) { if (xb_ld(&(bar)[XB_TMO])) break; if (_sp > XB_SPIN_CAP) { atomicAdd(&(bar)[XB_TMO], 1u); break; } } } } while (0)
; __device__ __forceinline__ bool is_leader(int wave_s) { int lane; asm volatile("v_mbcnt_lo_u32_b32 %0, -1, 0\n\tv_mbcnt_hi_u32_b32 %0, -1, %0" : "=v"(lane)); return wave_s == 0 && lane == 0; }
; __device__ __forceinline__ void grid_bar(unsigned* bar, volatile LAS unsigned* st, int wave_s, unsigned G) {
;     asm volatile("s_waitcnt vmcnt(0) lgkmcnt(0)" ::: "memory");
;     __syncthreads();
;     if (is_leader(wave_s)) {
;         const unsigned x = xb_xcc_id();
;         unsigned nloc = st[0], nx = st[1];
;         if (nloc == 0u) { xcd_barrier_complete(bar, x, G, nloc, nx); st[0] = nloc; st[1] = nx; }
;         const unsigned old = xb_add(&bar[XB_XSUB(x)], 1u);
;         const unsigned gen = old / nloc;
;         if (old + 1u == (gen + 1u) * nloc) {
;             __builtin_amdgcn_fence(__ATOMIC_RELEASE, "agent");
;             asm volatile("s_waitcnt vmcnt(0)" ::: "memory");
;             const unsigned og = xb_add(&bar[XB_TOP], 1u);
;             const unsigned tg = og / nx;
;             if (og + 1u == (tg + 1u) * nx) xb_add(&bar[XB_TOPGEN], 1u);
;             else XB_SPIN(xb_ld(&bar[XB_TOPGEN]) == tg, bar);
;             __builtin_amdgcn_fence(__ATOMIC_ACQUIRE, "agent");
;             xb_add(&bar[XB_XGEN(x)], 1u);
;             asm volatile("s_waitcnt vmcnt(0)" ::: "memory");
;         } else {
;             XB_SPIN(xb_ld(&bar[XB_XGEN(x)]) == gen, bar);
;             __builtin_amdgcn_fence(__ATOMIC_ACQUIRE, "agent");
;             asm volatile("s_waitcnt vmcnt(0)" ::: "memory");
;         }
;     }
;     __syncthreads();
; }
.LBB0_1132:
	s_mov_b32 s4, s95
	s_mov_b32 s2, s94
	s_cmp_lt_i32 s2, 11
	s_cselect_b64 s[2:3], -1, 0
	s_cmp_gt_i32 s4, 10
	s_cselect_b64 s[4:5], -1, 0
	s_and_b64 s[2:3], s[2:3], s[4:5]
	s_andn2_b64 vcc, exec, s[2:3]
	s_cbranch_vccnz .LBB0_1187
	s_mov_b32 s4, s95
	s_mov_b32 s2, s94
	s_cmp_lt_i32 s2, 12
	s_cselect_b64 s[2:3], -1, 0
	s_cmp_gt_i32 s4, 11
	s_cselect_b64 s[4:5], -1, 0
	s_and_b64 s[2:3], s[2:3], s[4:5]
	s_andn2_b64 vcc, exec, s[2:3]
	s_cbranch_vccnz .LBB0_1187
	s_cmp_lt_u32 s79, 64
	s_waitcnt vmcnt(0) lgkmcnt(0)
	s_cselect_b64 s[2:3], -1, 0
	s_waitcnt vmcnt(0) lgkmcnt(0)
	s_barrier
	v_mbcnt_lo_u32_b32 v0, -1, 0
	v_mbcnt_hi_u32_b32 v0, -1, v0
	s_nop 0
	v_cmp_eq_u32_e32 vcc, 0, v0
	s_and_b64 s[4:5], s[2:3], vcc
	s_and_saveexec_b64 s[2:3], s[4:5]
	s_cbranch_execz .LBB0_1186
	s_cmp_eq_u32 s98, 0
	s_cbranch_scc1 .Lgl_5
	s_load_dwordx2 s[4:5], s[0:1], 0xf0
	s_and_b32 s6, s78, 7
	s_lshl_b32 s6, s6, 8
	s_lshr_b32 s7, s92, 3
	s_mul_i32 s7, s7, 5
	v_mov_b32_e32 v0, s6
	v_mov_b32_e32 v1, 1
	s_waitcnt lgkmcnt(0)
	global_atomic_add v2, v0, v1, s[4:5] offset:1152 sc0
	s_waitcnt vmcnt(0)
	v_readfirstlane_b32 s8, v2
	s_add_i32 s8, s8, 1
	s_cmp_eq_u32 s8, s7
	s_cbranch_scc0 .Lwt_5
	global_atomic_add v0, v1, s[4:5] offset:1216
	s_branch .Lac_5
.Lwt_5:
	s_sleep 1
	global_load_dword v2, v0, s[4:5] offset:1216 sc1
	s_waitcnt vmcnt(0)
	v_readfirstlane_b32 s8, v2
	s_cmp_lt_u32 s8, 5
	s_cbranch_scc1 .Lwt_5

; #define LAS __attribute__((address_space(3)))
; __device__ __forceinline__ unsigned xb_ld(unsigned* p)              { return __hip_atomic_load(p, __ATOMIC_RELAXED, __HIP_MEMORY_SCOPE_AGENT); }
; __device__ __forceinline__ unsigned xb_add(unsigned* p, unsigned v) { return __hip_atomic_fetch_add(p, v, __ATOMIC_RELAXED, __HIP_MEMORY_SCOPE_AGENT); }
; __device__ __forceinline__ unsigned xb_xcc_id() { return (unsigned)__builtin_amdgcn_s_getreg((3 << 11) | 20) & 0xFu; }
; #define XB_SPIN(cond, bar) do { unsigned _sp = 0; while (cond) { __builtin_amdgcn_s_sleep(1); \
;     if ((++_sp & 255u) == 0u) { if (xb_ld(&(bar)[XB_TMO])) break; if (_sp > XB_SPIN_CAP) { atomicAdd(&(bar)[XB_TMO], 1u); break; } } } } while (0)
; __device__ __forceinline__ bool is_leader(int wave_s) { int lane; asm volatile("v_mbcnt_lo_u32_b32 %0, -1, 0\n\tv_mbcnt_hi_u32_b32 %0, -1, %0" : "=v"(lane)); return wave_s == 0 && lane == 0; }
; __device__ __forceinline__ void grid_bar(unsigned* bar, volatile LAS unsigned* st, int wave_s, unsigned G) {
;     asm volatile("s_waitcnt vmcnt(0) lgkmcnt(0)" ::: "memory");
;     __syncthreads();
;     if (is_leader(wave_s)) {
;         const unsigned x = xb_xcc_id();
;         unsigned nloc = st[0], nx = st[1];
;         if (nloc == 0u) { xcd_barrier_complete(bar, x, G, nloc, nx); st[0] = nloc; st[1] = nx; }
;         const unsigned old = xb_add(&bar[XB_XSUB(x)], 1u);
;         const unsigned gen = old / nloc;
;         if (old + 1u == (gen + 1u) * nloc) {
;             __builtin_amdgcn_fence(__ATOMIC_RELEASE, "agent");
;             asm volatile("s_waitcnt vmcnt(0)" ::: "memory");
;             const unsigned og = xb_add(&bar[XB_TOP], 1u);
;             const unsigned tg = og / nx;
;             if (og + 1u == (tg + 1u) * nx) xb_add(&bar[XB_TOPGEN], 1u);
;             else XB_SPIN(xb_ld(&bar[XB_TOPGEN]) == tg, bar);
;             __builtin_amdgcn_fence(__ATOMIC_ACQUIRE, "agent");
;             xb_add(&bar[XB_XGEN(x)], 1u);
;             asm volatile("s_waitcnt vmcnt(0)" ::: "memory");
;         } else {
;             XB_SPIN(xb_ld(&bar[XB_XGEN(x)]) == gen, bar);
;             __builtin_amdgcn_fence(__ATOMIC_ACQUIRE, "agent");
;             asm volatile("s_waitcnt vmcnt(0)" ::: "memory");
;         }
;     }
;     __syncthreads();
; }
.LBB0_1236:
	s_mov_b32 s2, s94
	s_mov_b32 s4, s95
	s_cmp_lt_i32 s2, 12
	s_cselect_b64 s[2:3], -1, 0
	s_cmp_gt_i32 s4, 11
	s_cselect_b64 s[4:5], -1, 0
	s_and_b64 s[2:3], s[2:3], s[4:5]
	s_andn2_b64 vcc, exec, s[2:3]
	s_cbranch_vccnz .LBB0_1291
	s_mov_b32 s2, s94
	s_mov_b32 s4, s95
	s_cmp_lt_i32 s2, 13
	s_cselect_b64 s[2:3], -1, 0
	s_cmp_gt_i32 s4, 12
	s_cselect_b64 s[4:5], -1, 0
	s_and_b64 s[2:3], s[2:3], s[4:5]
	s_andn2_b64 vcc, exec, s[2:3]
	s_cbranch_vccnz .LBB0_1291
	s_cmp_lt_u32 s79, 64
	s_waitcnt vmcnt(0) lgkmcnt(0)
	s_cselect_b64 s[2:3], -1, 0
	s_waitcnt vmcnt(0) lgkmcnt(0)
	s_barrier
	v_mbcnt_lo_u32_b32 v0, -1, 0
	v_mbcnt_hi_u32_b32 v0, -1, v0
	s_nop 0
	v_cmp_eq_u32_e32 vcc, 0, v0
	s_and_b64 s[4:5], s[2:3], vcc
	s_and_saveexec_b64 s[2:3], s[4:5]
	s_cbranch_execz .LBB0_1290
	s_cmp_eq_u32 s98, 0
	s_cbranch_scc1 .Lgl_6
	s_load_dwordx2 s[4:5], s[0:1], 0xf0
	s_and_b32 s6, s78, 7
	s_lshl_b32 s6, s6, 8
	s_lshr_b32 s7, s92, 3
	s_mul_i32 s7, s7, 6
	v_mov_b32_e32 v0, s6
	v_mov_b32_e32 v1, 1
	s_waitcnt lgkmcnt(0)
	global_atomic_add v2, v0, v1, s[4:5] offset:1152 sc0
	s_waitcnt vmcnt(0)
	v_readfirstlane_b32 s8, v2
	s_add_i32 s8, s8, 1
	s_cmp_eq_u32 s8, s7
	s_cbranch_scc0 .Lwt_6
	global_atomic_add v0, v1, s[4:5] offset:1216
	s_branch .Lac_6
.Lwt_6:
	s_sleep 1
	global_load_dword v2, v0, s[4:5] offset:1216 sc1
	s_waitcnt vmcnt(0)
	v_readfirstlane_b32 s8, v2
	s_cmp_lt_u32 s8, 6
	s_cbranch_scc1 .Lwt_6

; #define LAS __attribute__((address_space(3)))
; __device__ __forceinline__ unsigned xb_ld(unsigned* p)              { return __hip_atomic_load(p, __ATOMIC_RELAXED, __HIP_MEMORY_SCOPE_AGENT); }
; __device__ __forceinline__ unsigned xb_add(unsigned* p, unsigned v) { return __hip_atomic_fetch_add(p, v, __ATOMIC_RELAXED, __HIP_MEMORY_SCOPE_AGENT); }
; __device__ __forceinline__ unsigned xb_xcc_id() { return (unsigned)__builtin_amdgcn_s_getreg((3 << 11) | 20) & 0xFu; }
; #define XB_SPIN(cond, bar) do { unsigned _sp = 0; while (cond) { __builtin_amdgcn_s_sleep(1); \
;     if ((++_sp & 255u) == 0u) { if (xb_ld(&(bar)[XB_TMO])) break; if (_sp > XB_SPIN_CAP) { atomicAdd(&(bar)[XB_TMO], 1u); break; } } } } while (0)
; __device__ __forceinline__ bool is_leader(int wave_s) { int lane; asm volatile("v_mbcnt_lo_u32_b32 %0, -1, 0\n\tv_mbcnt_hi_u32_b32 %0, -1, %0" : "=v"(lane)); return wave_s == 0 && lane == 0; }
; __device__ __forceinline__ void grid_bar(unsigned* bar, volatile LAS unsigned* st, int wave_s, unsigned G) {
;     asm volatile("s_waitcnt vmcnt(0) lgkmcnt(0)" ::: "memory");
;     __syncthreads();
;     if (is_leader(wave_s)) {
;         const unsigned x = xb_xcc_id();
;         unsigned nloc = st[0], nx = st[1];
;         if (nloc == 0u) { xcd_barrier_complete(bar, x, G, nloc, nx); st[0] = nloc; st[1] = nx; }
;         const unsigned old = xb_add(&bar[XB_XSUB(x)], 1u);
;         const unsigned gen = old / nloc;
;         if (old + 1u == (gen + 1u) * nloc) {
;             __builtin_amdgcn_fence(__ATOMIC_RELEASE, "agent");
;             asm volatile("s_waitcnt vmcnt(0)" ::: "memory");
;             const unsigned og = xb_add(&bar[XB_TOP], 1u);
;             const unsigned tg = og / nx;
;             if (og + 1u == (tg + 1u) * nx) xb_add(&bar[XB_TOPGEN], 1u);
;             else XB_SPIN(xb_ld(&bar[XB_TOPGEN]) == tg, bar);
;             __builtin_amdgcn_fence(__ATOMIC_ACQUIRE, "agent");
;             xb_add(&bar[XB_XGEN(x)], 1u);
;             asm volatile("s_waitcnt vmcnt(0)" ::: "memory");
;         } else {
;             XB_SPIN(xb_ld(&bar[XB_XGEN(x)]) == gen, bar);
;             __builtin_amdgcn_fence(__ATOMIC_ACQUIRE, "agent");
;             asm volatile("s_waitcnt vmcnt(0)" ::: "memory");
;         }
;     }
;     __syncthreads();
; }
.LBB0_1832:
	s_mov_b32 s2, s94
	s_mov_b32 s4, s95
	s_cmp_lt_i32 s2, 19
	s_cselect_b64 s[2:3], -1, 0
	s_cmp_gt_i32 s4, 18
	s_cselect_b64 s[4:5], -1, 0
	s_and_b64 s[2:3], s[2:3], s[4:5]
	s_andn2_b64 vcc, exec, s[2:3]
	s_cbranch_vccnz .LBB0_1887
	s_mov_b32 s2, s94
	s_mov_b32 s4, s95
	s_cmp_lt_i32 s2, 20
	s_cselect_b64 s[2:3], -1, 0
	s_cmp_gt_i32 s4, 19
	s_cselect_b64 s[4:5], -1, 0
	s_and_b64 s[2:3], s[2:3], s[4:5]
	s_andn2_b64 vcc, exec, s[2:3]
	s_cbranch_vccnz .LBB0_1887
	s_cmp_lt_u32 s79, 64
	s_waitcnt vmcnt(0) lgkmcnt(0)
	s_cselect_b64 s[2:3], -1, 0
	s_waitcnt vmcnt(0) lgkmcnt(0)
	s_barrier
	v_mbcnt_lo_u32_b32 v0, -1, 0
	v_mbcnt_hi_u32_b32 v0, -1, v0
	s_nop 0
	v_cmp_eq_u32_e32 vcc, 0, v0
	s_and_b64 s[4:5], s[2:3], vcc
	s_and_saveexec_b64 s[2:3], s[4:5]
	s_cbranch_execz .LBB0_1886
	s_cmp_eq_u32 s98, 0
	s_cbranch_scc1 .Lgl_7
	s_load_dwordx2 s[4:5], s[0:1], 0xf0
	s_and_b32 s6, s78, 7
	s_lshl_b32 s6, s6, 8
	s_lshr_b32 s7, s92, 3
	s_mul_i32 s7, s7, 7
	v_mov_b32_e32 v0, s6
	v_mov_b32_e32 v1, 1
	s_waitcnt lgkmcnt(0)
	global_atomic_add v2, v0, v1, s[4:5] offset:1152 sc0
	s_waitcnt vmcnt(0)
	v_readfirstlane_b32 s8, v2
	s_add_i32 s8, s8, 1
	s_cmp_eq_u32 s8, s7
	s_cbranch_scc0 .Lwt_7
	global_atomic_add v0, v1, s[4:5] offset:1216
	s_branch .Lac_7
.Lwt_7:
	s_sleep 1
	global_load_dword v2, v0, s[4:5] offset:1216 sc1
	s_waitcnt vmcnt(0)
	v_readfirstlane_b32 s8, v2
	s_cmp_lt_u32 s8, 7
	s_cbranch_scc1 .Lwt_7

; #define LAS __attribute__((address_space(3)))
; __device__ __forceinline__ unsigned xb_ld(unsigned* p)              { return __hip_atomic_load(p, __ATOMIC_RELAXED, __HIP_MEMORY_SCOPE_AGENT); }
; __device__ __forceinline__ unsigned xb_add(unsigned* p, unsigned v) { return __hip_atomic_fetch_add(p, v, __ATOMIC_RELAXED, __HIP_MEMORY_SCOPE_AGENT); }
; __device__ __forceinline__ unsigned xb_xcc_id() { return (unsigned)__builtin_amdgcn_s_getreg((3 << 11) | 20) & 0xFu; }
; #define XB_SPIN(cond, bar) do { unsigned _sp = 0; while (cond) { __builtin_amdgcn_s_sleep(1); \
;     if ((++_sp & 255u) == 0u) { if (xb_ld(&(bar)[XB_TMO])) break; if (_sp > XB_SPIN_CAP) { atomicAdd(&(bar)[XB_TMO], 1u); break; } } } } while (0)
; __device__ __forceinline__ bool is_leader(int wave_s) { int lane; asm volatile("v_mbcnt_lo_u32_b32 %0, -1, 0\n\tv_mbcnt_hi_u32_b32 %0, -1, %0" : "=v"(lane)); return wave_s == 0 && lane == 0; }
; __device__ __forceinline__ void grid_bar(unsigned* bar, volatile LAS unsigned* st, int wave_s, unsigned G) {
;     asm volatile("s_waitcnt vmcnt(0) lgkmcnt(0)" ::: "memory");
;     __syncthreads();
;     if (is_leader(wave_s)) {
;         const unsigned x = xb_xcc_id();
;         unsigned nloc = st[0], nx = st[1];
;         if (nloc == 0u) { xcd_barrier_complete(bar, x, G, nloc, nx); st[0] = nloc; st[1] = nx; }
;         const unsigned old = xb_add(&bar[XB_XSUB(x)], 1u);
;         const unsigned gen = old / nloc;
;         if (old + 1u == (gen + 1u) * nloc) {
;             __builtin_amdgcn_fence(__ATOMIC_RELEASE, "agent");
;             asm volatile("s_waitcnt vmcnt(0)" ::: "memory");
;             const unsigned og = xb_add(&bar[XB_TOP], 1u);
;             const unsigned tg = og / nx;
;             if (og + 1u == (tg + 1u) * nx) xb_add(&bar[XB_TOPGEN], 1u);
;             else XB_SPIN(xb_ld(&bar[XB_TOPGEN]) == tg, bar);
;             __builtin_amdgcn_fence(__ATOMIC_ACQUIRE, "agent");
;             xb_add(&bar[XB_XGEN(x)], 1u);
;             asm volatile("s_waitcnt vmcnt(0)" ::: "memory");
;         } else {
;             XB_SPIN(xb_ld(&bar[XB_XGEN(x)]) == gen, bar);
;             __builtin_amdgcn_fence(__ATOMIC_ACQUIRE, "agent");
;             asm volatile("s_waitcnt vmcnt(0)" ::: "memory");
;         }
;     }
;     __syncthreads();
; }
.LBB0_1962:
	s_mov_b32 s2, s94
	s_mov_b32 s4, s95
	s_cmp_lt_i32 s2, 20
	s_cselect_b64 s[2:3], -1, 0
	s_cmp_gt_i32 s4, 19
	s_cselect_b64 s[4:5], -1, 0
	s_and_b64 s[2:3], s[2:3], s[4:5]
	s_andn2_b64 vcc, exec, s[2:3]
	s_cbranch_vccnz .LBB0_2017
	s_mov_b32 s2, s94
	s_mov_b32 s4, s95
	s_cmp_lt_i32 s2, 21
	s_cselect_b64 s[2:3], -1, 0
	s_cmp_gt_i32 s4, 20
	s_cselect_b64 s[4:5], -1, 0
	s_and_b64 s[2:3], s[2:3], s[4:5]
	s_andn2_b64 vcc, exec, s[2:3]
	s_cbranch_vccnz .LBB0_2017
	s_cmp_lt_u32 s79, 64
	s_waitcnt vmcnt(0) lgkmcnt(0)
	s_cselect_b64 s[2:3], -1, 0
	s_waitcnt vmcnt(0) lgkmcnt(0)
	s_barrier
	v_mbcnt_lo_u32_b32 v0, -1, 0
	v_mbcnt_hi_u32_b32 v0, -1, v0
	s_nop 0
	v_cmp_eq_u32_e32 vcc, 0, v0
	s_and_b64 s[4:5], s[2:3], vcc
	s_and_saveexec_b64 s[2:3], s[4:5]
	s_cbranch_execz .LBB0_2016
	s_cmp_eq_u32 s98, 0
	s_cbranch_scc1 .Lgl_8
	s_load_dwordx2 s[4:5], s[0:1], 0xf0
	s_and_b32 s6, s78, 7
	s_lshl_b32 s6, s6, 8
	s_lshr_b32 s7, s92, 3
	s_mul_i32 s7, s7, 8
	v_mov_b32_e32 v0, s6
	v_mov_b32_e32 v1, 1
	s_waitcnt lgkmcnt(0)
	global_atomic_add v2, v0, v1, s[4:5] offset:1152 sc0
	s_waitcnt vmcnt(0)
	v_readfirstlane_b32 s8, v2
	s_add_i32 s8, s8, 1
	s_cmp_eq_u32 s8, s7
	s_cbranch_scc0 .Lwt_8
	global_atomic_add v0, v1, s[4:5] offset:1216
	s_branch .Lac_8
.Lwt_8:
	s_sleep 1
	global_load_dword v2, v0, s[4:5] offset:1216 sc1
	s_waitcnt vmcnt(0)
	v_readfirstlane_b32 s8, v2
	s_cmp_lt_u32 s8, 8
	s_cbranch_scc1 .Lwt_8

; #define LAS __attribute__((address_space(3)))
; __global__ void __launch_bounds__(512, 2) mk_fwd(Args args) {
;     extern __shared__ __attribute__((aligned(16))) unsigned char lds_raw[];
;     LAS unsigned char* lds = (LAS unsigned char*)lds_raw;
;     const int G = gridDim.x;
;     const int wave_s = __builtin_amdgcn_readfirstlane(threadIdx.x >> 6);
	.amdhsa_kernel _Z6mk_fwd4Args
		.amdhsa_group_segment_fixed_size 0
		.amdhsa_private_segment_fixed_size 0
		.amdhsa_kernarg_size 1864
		.amdhsa_user_sgpr_count 2
		.amdhsa_user_sgpr_dispatch_ptr 0
		.amdhsa_user_sgpr_queue_ptr 0
		.amdhsa_user_sgpr_kernarg_segment_ptr 1
		.amdhsa_user_sgpr_dispatch_id 0
		.amdhsa_user_sgpr_kernarg_preload_length 0
		.amdhsa_user_sgpr_kernarg_preload_offset 0
		.amdhsa_user_sgpr_private_segment_size 0
		.amdhsa_uses_dynamic_stack 0
		.amdhsa_enable_private_segment 0
		.amdhsa_system_sgpr_workgroup_id_x 1
		.amdhsa_system_sgpr_workgroup_id_y 0
		.amdhsa_system_sgpr_workgroup_id_z 0
		.amdhsa_system_sgpr_workgroup_info 0
		.amdhsa_system_vgpr_workitem_id 2
		.amdhsa_next_free_vgpr 244
		.amdhsa_next_free_sgpr 100
		.amdhsa_accum_offset 244
		.amdhsa_reserve_vcc 1
		.amdhsa_float_round_mode_32 0
		.amdhsa_float_round_mode_16_64 0
		.amdhsa_float_denorm_mode_32 3
		.amdhsa_float_denorm_mode_16_64 3
		.amdhsa_dx10_clamp 1
		.amdhsa_ieee_mode 1
		.amdhsa_fp16_overflow 0
		.amdhsa_tg_split 0
		.amdhsa_exception_fp_ieee_invalid_op 0
		.amdhsa_exception_fp_denorm_src 0
		.amdhsa_exception_fp_ieee_div_zero 0
		.amdhsa_exception_fp_ieee_overflow 0
		.amdhsa_exception_fp_ieee_underflow 0
		.amdhsa_exception_fp_ieee_inexact 0
		.amdhsa_exception_int_div_zero 0
	.end_amdhsa_kernel

; #define LAS __attribute__((address_space(3)))
; __global__ void __launch_bounds__(512, 2) mk_fwd(Args args) {
;     extern __shared__ __attribute__((aligned(16))) unsigned char lds_raw[];
;     LAS unsigned char* lds = (LAS unsigned char*)lds_raw;
;     const int G = gridDim.x;
;     const int wave_s = __builtin_amdgcn_readfirstlane(threadIdx.x >> 6);
amdhsa.kernels:
  - .agpr_count:     0
    .args:
      - .offset:         0
        .size:           1608
        .value_kind:     by_value
      - .offset:         1608
        .size:           4
        .value_kind:     hidden_block_count_x
      - .offset:         1612
        .size:           4
        .value_kind:     hidden_block_count_y
      - .offset:         1616
        .size:           4
        .value_kind:     hidden_block_count_z
      - .offset:         1620
        .size:           2
        .value_kind:     hidden_group_size_x
      - .offset:         1622
        .size:           2
        .value_kind:     hidden_group_size_y
      - .offset:         1624
        .size:           2
        .value_kind:     hidden_group_size_z
      - .offset:         1626
        .size:           2
        .value_kind:     hidden_remainder_x
      - .offset:         1628
        .size:           2
        .value_kind:     hidden_remainder_y
      - .offset:         1630
        .size:           2
        .value_kind:     hidden_remainder_z
      - .offset:         1648
        .size:           8
        .value_kind:     hidden_global_offset_x
      - .offset:         1656
        .size:           8
        .value_kind:     hidden_global_offset_y
      - .offset:         1664
        .size:           8
        .value_kind:     hidden_global_offset_z
      - .offset:         1672
        .size:           2
        .value_kind:     hidden_grid_dims
      - .offset:         1696
        .size:           8
        .value_kind:     hidden_multigrid_sync_arg
      - .offset:         1728
        .size:           4
        .value_kind:     hidden_dynamic_lds_size
    .group_segment_fixed_size: 0
    .kernarg_segment_align: 8
    .kernarg_segment_size: 1864
    .language:       OpenCL C
    .language_version:
      - 2
      - 0
    .max_flat_workgroup_size: 512
    .name:           _Z6mk_fwd4Args
    .private_segment_fixed_size: 0
    .sgpr_count:     106
    .sgpr_spill_count: 50
    .symbol:         _Z6mk_fwd4Args.kd
    .uniform_work_group_size: 1
    .uses_dynamic_stack: false
    .vgpr_count:     244
    .vgpr_spill_count: 0
    .wavefront_size: 64
